# SSD diagonal pass item: C-fragment loads issued right after the tile LDS writes (overlapping the dt round trip and the scan) instead of after them; on top of v37
# speedup vs baseline: 1.0066x; 1.0066x over previous
; __device__ __forceinline__ int tid_() { int t = threadIdx.x; asm volatile("" : "+v"(t)); return t; }
; __device__ __forceinline__ void ssd_diag_item(CParams& p, int j2, int row0, int h, bf16_t* smem) {
;     const int tid = tid_(), lane = tid & 63, wave = tid >> 6, l16 = lane & 15, quad = lane >> 4;
;     const int g = h >> 3;
;     bf16_t* sB = smem;
;     bf16_t* sX = sB + 128 * SST;
;     float* sda = (float*)(sX + 64 * SST);
;     float* sPf = sda + 256;
;     float* sRb = sPf + 128;
;     float* sdtf = sRb + 128;
;     float* sdtb = sdtf + 128;
;     float* scolF = sdtb + 128;
;     float* scolB = scolF + 128;
;     const bf16_t* XT = (const bf16_t*)(p.ws + WS_XT) + (size_t)(h * 64) * MT;
;     const bf16_t* Bn = (const bf16_t*)(p.ws + WS_BN) + g * 128;
;     const bf16_t* Cn = (const bf16_t*)(p.ws + WS_CN) + (size_t)(g * 4) * 512;
;     const float* DT = (const float*)(p.ws + WS_DT);
;     bf16_t* Y = (bf16_t*)(p.ws + WS_YF);
;     const float af = -expf(p.ssm_a_log[(j2 * 2 + 0) * 32 + h]);
;     const float ab = -expf(p.ssm_a_log[(j2 * 2 + 1) * 32 + h]);
;     const float dsk = p.ssm_d[j2 * 32 + h];
;     lds_sync();
; #pragma unroll
;     for (int i = 0; i < 8; ++i) {
;         const int c = tid + i * 256, r = c >> 4, kc = (c & 15) * 8;
;         *(u32x4*)(sB + r * SST + kc) = *(const u32x4*)(Bn + (size_t)(row0 + r) * 512 + kc);
;     }
; #pragma unroll
;     for (int i = 0; i < 4; ++i) {
;         const int c = tid + i * 256, r = c >> 4, kc = (c & 15) * 8;
;         *(u32x4*)(sX + r * SST + kc) = *(const u32x4*)(XT + (size_t)r * MT + row0 + kc);
;     }
.LBB0_425:
	s_lshl_b32 s8, s22, 2
	s_bfe_u32 s24, s22, 0x20003
	s_and_b32 s23, s22, 31
	s_and_b32 s8, s8, 0xffffff80
	s_lshl_b32 s9, s24, 8
	s_add_u32 s12, s16, s9
	s_addc_u32 s13, s17, 0
	s_or_b32 s78, s23, s18
	s_waitcnt vmcnt(27)
	v_mov_b32_e32 v1, v167
	s_lshl_b64 s[26:27], s[78:79], 2
	s_add_u32 s26, s52, s26
	v_lshlrev_b32_e32 v2, 4, v1
	s_waitcnt vmcnt(20)
	v_ashrrev_i32_e32 v21, 4, v1
	s_addc_u32 s27, s53, s27
	s_or_b32 s78, s23, s19
	v_and_b32_e32 v164, 0xf0, v2
	v_add_u32_e32 v2, s8, v21
	global_load_dword v9, v165, s[26:27]
	global_load_dword v20, v165, s[26:27] offset:128
	s_lshl_b64 s[26:27], s[78:79], 2
	v_ashrrev_i32_e32 v3, 31, v2
	s_add_u32 s26, s54, s26
	v_lshl_add_u64 v[6:7], s[12:13], 0, v[164:165]
	v_lshlrev_b64 v[2:3], 10, v[2:3]
	s_addc_u32 s27, s55, s27
	v_lshl_add_u64 v[2:3], v[6:7], 0, v[2:3]
	global_load_dword v96, v165, s[26:27]
	s_waitcnt vmcnt(63) expcnt(7) lgkmcnt(15)
	s_barrier
	global_load_dwordx4 v[140:143], v[2:3], off
	v_add_u32_e32 v8, 0, v164
	s_mov_b32 s27, 0x3fb8aa3b
	s_mul_i32 s9, s23, 0x210000
	s_add_u32 s25, s14, s9
	s_addc_u32 s26, s15, 0
	s_ashr_i32 s9, s8, 31
	s_mov_b32 s39, 0xc2ce8ed0
	s_mov_b32 s2, 0x42b17218
	v_and_b32_e32 v0, 63, v1
	s_mov_b32 s28, 0x3fb8aa3b
	s_mov_b32 s90, 0xc2ce8ed0
	s_mov_b32 s89, 0x42b17218
	s_waitcnt vmcnt(3)
	v_mad_u64_u32 v[10:11], s[12:13], v21, s91, v[8:9]
	v_cmp_ngt_f32_e32 vcc, s39, v9
	v_add_u32_e32 v2, 0x100, v1
	v_ashrrev_i32_e32 v11, 4, v2
	v_add_u32_e32 v2, s8, v11
	v_ashrrev_i32_e32 v3, 31, v2
	v_lshlrev_b64 v[2:3], 10, v[2:3]
	v_lshl_add_u64 v[2:3], v[6:7], 0, v[2:3]
	global_load_dwordx4 v[144:147], v[2:3], off
	v_mad_u64_u32 v[12:13], s[12:13], v11, s91, v[8:9]
	v_add_u32_e32 v2, 0x200, v1
	v_ashrrev_i32_e32 v13, 4, v2
	v_add_u32_e32 v2, s8, v13
	v_ashrrev_i32_e32 v3, 31, v2
	v_lshlrev_b64 v[2:3], 10, v[2:3]
	v_lshl_add_u64 v[2:3], v[6:7], 0, v[2:3]
	global_load_dwordx4 v[148:151], v[2:3], off
	v_mad_u64_u32 v[14:15], s[12:13], v13, s91, v[8:9]
	v_add_u32_e32 v2, 0x300, v1
	v_ashrrev_i32_e32 v15, 4, v2
	v_add_u32_e32 v2, s8, v15
	v_ashrrev_i32_e32 v3, 31, v2
	v_lshlrev_b64 v[2:3], 10, v[2:3]
	v_lshl_add_u64 v[2:3], v[6:7], 0, v[2:3]
	global_load_dwordx4 v[152:155], v[2:3], off
	v_mad_u64_u32 v[16:17], s[12:13], v15, s91, v[8:9]
	v_add_u32_e32 v2, 0x400, v1
	v_ashrrev_i32_e32 v17, 4, v2
	v_add_u32_e32 v2, s8, v17
	v_ashrrev_i32_e32 v3, 31, v2
	v_lshlrev_b64 v[2:3], 10, v[2:3]
	v_lshl_add_u64 v[2:3], v[6:7], 0, v[2:3]
	global_load_dwordx4 v[156:159], v[2:3], off
	v_mad_u64_u32 v[224:225], s[12:13], v17, s91, v[8:9]
	v_add_u32_e32 v2, 0x500, v1
	v_ashrrev_i32_e32 v17, 4, v2
	v_add_u32_e32 v2, s8, v17
	v_ashrrev_i32_e32 v3, 31, v2
	v_lshlrev_b64 v[2:3], 10, v[2:3]
	v_lshl_add_u64 v[2:3], v[6:7], 0, v[2:3]
	global_load_dwordx4 v[160:163], v[2:3], off
	v_mad_u64_u32 v[226:227], s[12:13], v17, s91, v[8:9]
	v_add_u32_e32 v2, 0x600, v1
	v_ashrrev_i32_e32 v17, 4, v2
	v_add_u32_e32 v2, s8, v17
	v_ashrrev_i32_e32 v3, 31, v2
	v_lshlrev_b64 v[2:3], 10, v[2:3]
	v_lshl_add_u64 v[2:3], v[6:7], 0, v[2:3]
	global_load_dwordx4 v[172:175], v[2:3], off
	v_mad_u64_u32 v[228:229], s[12:13], v17, s91, v[8:9]
	v_add_u32_e32 v2, 0x700, v1
	v_ashrrev_i32_e32 v17, 4, v2
	v_add_u32_e32 v2, s8, v17
	v_ashrrev_i32_e32 v3, 31, v2
	v_lshlrev_b64 v[2:3], 10, v[2:3]
	v_lshl_add_u64 v[2:3], v[6:7], 0, v[2:3]
	global_load_dwordx4 v[176:179], v[2:3], off
	v_mad_u64_u32 v[230:231], s[12:13], v17, s91, v[8:9]
	s_lshl_b64 s[12:13], s[8:9], 1
	s_add_u32 s12, s25, s12
	s_addc_u32 s13, s26, s13
	s_lshl_b32 s78, s23, 2
	s_movk_i32 s9, 0x7f
	v_cmp_lt_u32_e64 s[42:43], s9, v1
	s_movk_i32 s9, 0x80
	v_mul_f32_e32 v2, 0x3fb8aa3b, v9
	v_fma_f32 v3, v9, s27, -v2
	v_rndne_f32_e32 v4, v2
	v_fmac_f32_e32 v3, 0x32a5705f, v9
	v_sub_f32_e32 v2, v2, v4
	v_add_f32_e32 v2, v2, v3
	v_exp_f32_e32 v2, v2
	v_cvt_i32_f32_e32 v3, v4
	v_lshl_add_u64 v[6:7], s[12:13], 0, v[164:165]
	v_ldexp_f32 v2, v2, v3
	v_cndmask_b32_e32 v2, 0, v2, vcc
	v_cmp_nlt_f32_e32 vcc, s2, v9
	s_nop 1
	v_cndmask_b32_e32 v17, v208, v2, vcc
	v_mad_i64_i32 v[2:3], s[12:13], v21, s40, v[6:7]
	global_load_dwordx4 v[180:183], v[2:3], off
	v_mad_i64_i32 v[2:3], s[12:13], v11, s40, v[6:7]
	global_load_dwordx4 v[184:187], v[2:3], off
	v_mad_i64_i32 v[2:3], s[12:13], v13, s40, v[6:7]
	global_load_dwordx4 v[188:191], v[2:3], off
	v_mad_i64_i32 v[2:3], s[12:13], v15, s40, v[6:7]
	global_load_dwordx4 v[220:223], v[2:3], off
	s_waitcnt vmcnt(11)
	ds_write_b128 v10, v[140:143]
	s_waitcnt vmcnt(10)
	ds_write_b128 v12, v[144:147]
	s_waitcnt vmcnt(9)
	ds_write_b128 v14, v[148:151]
	s_waitcnt vmcnt(8)
	ds_write_b128 v16, v[152:155]
	s_waitcnt vmcnt(7)
	ds_write_b128 v224, v[156:159]
	s_waitcnt vmcnt(6)
	ds_write_b128 v226, v[160:163]
	s_waitcnt vmcnt(5)
	ds_write_b128 v228, v[172:175]
	s_waitcnt vmcnt(4)
	ds_write_b128 v230, v[176:179]
	s_waitcnt vmcnt(3)
	ds_write_b128 v10, v[180:183] offset:34816
	s_waitcnt vmcnt(2)
; __device__ __forceinline__ f32x2 scan128(float s0, float s1, int lane, int dir) {
;     ...
;     } else {
; #pragma unroll
;         for (int o = 1; o < 64; o <<= 1) { const float t0 = __shfl_down(s0, o), t1 = __shfl_down(s1, o); s0 += lane + o < 64 ? t0 : 0.f; s1 += lane + o < 64 ? t1 : 0.f; }
;         s0 += __shfl(s1, 0);
;     }
; __device__ __forceinline__ void ssd_diag_item(CParams& p, int j2, int row0, int h, bf16_t* smem) {
;     ...
;     for (int i = 0; i < 4; ++i) {
;         const int c = tid + i * 256, r = c >> 4, kc = (c & 15) * 8;
;         *(u32x4*)(sX + r * SST + kc) = *(const u32x4*)(XT + (size_t)r * MT + row0 + kc);
;     }
;     {
;         const int d = wave >> 1;
;         const float d0 = DT[(size_t)(row0 + lane) * 64 + d * 32 + h], d1 = DT[(size_t)(row0 + 64 + lane) * 64 + d * 32 + h];
;         const float aa = d ? ab : af;
;         const f32x2 sc2 = scan128(d0 * aa, d1 * aa, lane, d);
;         float* sc = d ? sRb : sPf; float* sd = d ? sdtb : sdtf;
;         if ((wave & 1) == 0) { sc[lane] = sc2.x; sd[lane] = d0; } else { sc[64 + lane] = sc2.y; sd[64 + lane] = d1; }
;         const float own = (wave & 1) == 0 ? sc2.x : sc2.y;
;         const float ref = __shfl(own, d == 0 ? (lane | 7) : (lane & ~7));
;         float* scol = d ? scolB : scolF;
;         scol[(wave & 1) * 64 + lane] = ((wave & 1) == 0 ? d0 : d1) * __expf(ref - own);
;     }
;     bf16x8 cf[2][4];
; #pragma unroll
;     for (int i = 0; i < 2; ++i)
; #pragma unroll
;         for (int ks = 0; ks < 4; ++ks)
;             cf[i][ks] = *(const bf16x8*)(Cn + ((size_t)((row0 >> 4) + wave * 2 + i) * 16 + ks) * 512 + lane * 8);
	ds_write_b128 v12, v[184:187] offset:34816
	s_waitcnt vmcnt(1)
	ds_write_b128 v14, v[188:191] offset:34816
	s_waitcnt vmcnt(0)
	ds_write_b128 v16, v[220:223] offset:34816
	s_lshl_b32 s12, s24, 12
	s_add_u32 s12, s20, s12
	s_addc_u32 s13, s21, 0
	s_ashr_i32 s25, s8, 4
	v_ashrrev_i32_e32 v232, 6, v1
	v_lshl_add_u32 v234, v232, 1, s25
	v_ashrrev_i32_e32 v235, 31, v234
	v_lshlrev_b32_e32 v240, 4, v0
	v_mov_b32_e32 v241, 0
	v_lshlrev_b64 v[236:237], 14, v[234:235]
	v_or_b32_e32 v238, 1, v234
	v_ashrrev_i32_e32 v239, 31, v238
	v_lshl_add_u64 v[244:245], s[12:13], 0, v[240:241]
	v_lshlrev_b64 v[242:243], 14, v[238:239]
	v_lshl_add_u64 v[236:237], v[244:245], 0, v[236:237]
	v_lshl_add_u64 v[242:243], v[244:245], 0, v[242:243]
	global_load_dwordx4 v[140:143], v[236:237], off
	global_load_dwordx4 v[144:147], v[236:237], off offset:1024
	global_load_dwordx4 v[148:151], v[236:237], off offset:2048
	global_load_dwordx4 v[152:155], v[236:237], off offset:3072
	global_load_dwordx4 v[156:159], v[242:243], off
	global_load_dwordx4 v[160:163], v[242:243], off offset:1024
	global_load_dwordx4 v[172:175], v[242:243], off offset:2048
	global_load_dwordx4 v[176:179], v[242:243], off offset:3072
	v_cmp_ngt_f32_e32 vcc, s39, v20
	v_mul_f32_e32 v2, 0x3fb8aa3b, v20
	v_fma_f32 v3, v20, s27, -v2
	v_rndne_f32_e32 v4, v2
	v_fmac_f32_e32 v3, 0x32a5705f, v20
	v_sub_f32_e32 v2, v2, v4
	v_add_f32_e32 v2, v2, v3
	v_exp_f32_e32 v2, v2
	v_cvt_i32_f32_e32 v3, v4
	v_or_b32_e32 v4, s8, v0
	v_ashrrev_i32_e32 v5, 31, v4
	v_lshlrev_b64 v[6:7], 8, v[4:5]
	v_ldexp_f32 v2, v2, v3
	v_cndmask_b32_e32 v2, 0, v2, vcc
	v_cmp_nlt_f32_e32 vcc, s2, v20
	v_or_b32_e32 v4, 64, v4
	v_ashrrev_i32_e32 v5, 31, v4
	v_cndmask_b32_e32 v10, v208, v2, vcc
	v_ashrrev_i32_e32 v2, 2, v1
	v_and_b32_e32 v2, 0xffffffe0, v2
	v_ashrrev_i32_e32 v3, 31, v2
	v_lshlrev_b64 v[4:5], 8, v[4:5]
	v_lshl_add_u64 v[6:7], s[4:5], 0, v[6:7]
	v_lshlrev_b64 v[8:9], 2, v[2:3]
	v_lshl_add_u64 v[4:5], s[4:5], 0, v[4:5]
	v_lshl_add_u64 v[2:3], v[6:7], 0, v[8:9]
	v_lshl_add_u64 v[4:5], v[4:5], 0, v[8:9]
	v_lshl_add_u64 v[2:3], v[2:3], 0, s[78:79]
	v_lshl_add_u64 v[4:5], v[4:5], 0, s[78:79]
	global_load_dword v2, v[2:3], off
	v_cmp_gt_u32_e32 vcc, s9, v1
	global_load_dword v3, v[4:5], off
	s_nop 0
	v_cndmask_b32_e32 v4, v10, v17, vcc
	s_waitcnt vmcnt(1)
	v_mul_f32_e64 v7, v2, -v4
	s_waitcnt vmcnt(0)
	v_mul_f32_e64 v6, v3, -v4
	s_and_saveexec_b64 s[12:13], s[42:43]
	s_xor_b64 s[12:13], exec, s[12:13]
	s_cbranch_execz .LBB0_427
	v_and_b32_e32 v4, 63, v197
	v_cmp_ne_u32_e64 s[42:43], 63, v4
	s_nop 1
	v_addc_co_u32_e64 v5, s[42:43], 0, v197, s[42:43]
	v_lshlrev_b32_e32 v5, 2, v5
	ds_bpermute_b32 v8, v5, v7
	ds_bpermute_b32 v5, v5, v6
	v_cmp_eq_u32_e64 s[42:43], 63, v0
	s_waitcnt lgkmcnt(1)
	s_nop 0
	v_cndmask_b32_e64 v8, v8, 0, s[42:43]
	s_waitcnt lgkmcnt(0)
	v_cndmask_b32_e64 v5, v5, 0, s[42:43]
	v_cmp_gt_u32_e64 s[42:43], 62, v4
	v_add_f32_e32 v5, v6, v5
	v_add_f32_e32 v7, v7, v8
	v_cndmask_b32_e64 v6, 0, 2, s[42:43]
	v_add_lshl_u32 v6, v6, v197, 2
	ds_bpermute_b32 v8, v6, v7
	ds_bpermute_b32 v6, v6, v5
	v_cmp_gt_u32_e64 s[42:43], 62, v0
	s_waitcnt lgkmcnt(1)
	s_nop 0
	v_cndmask_b32_e64 v8, 0, v8, s[42:43]
	s_waitcnt lgkmcnt(0)
	v_cndmask_b32_e64 v6, 0, v6, s[42:43]
	v_cmp_gt_u32_e64 s[42:43], 60, v4
	v_add_f32_e32 v5, v5, v6
	v_add_f32_e32 v7, v7, v8
	v_cndmask_b32_e64 v6, 0, 4, s[42:43]
	v_add_lshl_u32 v6, v6, v197, 2
	ds_bpermute_b32 v8, v6, v7
	ds_bpermute_b32 v6, v6, v5
	v_cmp_gt_u32_e64 s[42:43], 60, v0
	s_waitcnt lgkmcnt(1)
	s_nop 0
	v_cndmask_b32_e64 v8, 0, v8, s[42:43]
	s_waitcnt lgkmcnt(0)
	v_cndmask_b32_e64 v6, 0, v6, s[42:43]
	v_cmp_gt_u32_e64 s[42:43], 56, v4
	v_add_f32_e32 v5, v5, v6
	v_add_f32_e32 v7, v7, v8
	v_cndmask_b32_e64 v6, 0, 8, s[42:43]
	v_add_lshl_u32 v6, v6, v197, 2
	ds_bpermute_b32 v8, v6, v7
	ds_bpermute_b32 v6, v6, v5
	v_cmp_gt_u32_e64 s[42:43], 56, v0
	s_waitcnt lgkmcnt(1)
	s_nop 0
	v_cndmask_b32_e64 v8, 0, v8, s[42:43]
	s_waitcnt lgkmcnt(0)
	v_cndmask_b32_e64 v6, 0, v6, s[42:43]
	v_cmp_gt_u32_e64 s[42:43], 48, v4
	v_add_f32_e32 v7, v7, v8
	v_add_f32_e32 v5, v5, v6
	v_cndmask_b32_e64 v4, 0, 16, s[42:43]
	v_add_lshl_u32 v4, v4, v197, 2
	ds_bpermute_b32 v6, v4, v7
	ds_bpermute_b32 v4, v4, v5
	v_cmp_gt_u32_e64 s[42:43], 48, v0
	s_waitcnt lgkmcnt(1)
	s_nop 0
	v_cndmask_b32_e64 v6, 0, v6, s[42:43]
	v_add_f32_e32 v6, v7, v6
	s_waitcnt lgkmcnt(0)
	v_cndmask_b32_e64 v4, 0, v4, s[42:43]
	v_lshlrev_b32_e32 v7, 2, v197
	v_add_f32_e32 v4, v5, v4
	v_or_b32_e32 v5, 0x80, v7
	ds_bpermute_b32 v8, v5, v6
	ds_bpermute_b32 v5, v5, v4
	v_cmp_gt_u32_e64 s[42:43], 32, v0
	s_waitcnt lgkmcnt(1)
	s_nop 0
	v_cndmask_b32_e64 v8, 0, v8, s[42:43]
	s_waitcnt lgkmcnt(0)
	v_cndmask_b32_e64 v5, 0, v5, s[42:43]
	v_add_f32_e32 v5, v4, v5
	v_and_b32_e32 v4, 0x100, v7
	ds_bpermute_b32 v4, v4, v5
	v_add_f32_e32 v6, v6, v8
	s_waitcnt lgkmcnt(0)
	v_add_f32_e32 v4, v6, v4

; __device__ __forceinline__ void ssd_diag_item(CParams& p, int j2, int row0, int h, bf16_t* smem) {
;     ...
;     {
;         const int d = wave >> 1;
;         const float d0 = DT[(size_t)(row0 + lane) * 64 + d * 32 + h], d1 = DT[(size_t)(row0 + 64 + lane) * 64 + d * 32 + h];
;         const float aa = d ? ab : af;
;         const f32x2 sc2 = scan128(d0 * aa, d1 * aa, lane, d);
;         float* sc = d ? sRb : sPf; float* sd = d ? sdtb : sdtf;
;         if ((wave & 1) == 0) { sc[lane] = sc2.x; sd[lane] = d0; } else { sc[64 + lane] = sc2.y; sd[64 + lane] = d1; }
;         const float own = (wave & 1) == 0 ? sc2.x : sc2.y;
;         const float ref = __shfl(own, d == 0 ? (lane | 7) : (lane & ~7));
;         float* scol = d ? scolB : scolF;
;         scol[(wave & 1) * 64 + lane] = ((wave & 1) == 0 ? d0 : d1) * __expf(ref - own);
;     }
;     bf16x8 cf[2][4];
; #pragma unroll
;     for (int i = 0; i < 2; ++i)
; #pragma unroll
;         for (int ks = 0; ks < 4; ++ks)
;             cf[i][ks] = *(const bf16x8*)(Cn + ((size_t)((row0 >> 4) + wave * 2 + i) * 16 + ks) * 512 + lane * 8);
;     lds_sync();
;     float pfl[2], rbl[2];
; #pragma unroll
;     for (int i = 0; i < 2; ++i) { pfl[i] = sPf[wave * 32 + i * 16 + l16]; rbl[i] = sRb[wave * 32 + i * 16 + l16]; }
;     f32x4 y[4][2];
; #pragma unroll
;     for (int pt = 0; pt < 4; ++pt)
; #pragma unroll
;         for (int i = 0; i < 2; ++i) y[pt][i] = (f32x4){0.f, 0.f, 0.f, 0.f};
.LBB0_429:
	s_or_b64 exec, exec, s[12:13]
	v_ashrrev_i32_e32 v11, 6, v1
	v_and_b32_e32 v6, 1, v11
	v_cmp_eq_u32_e64 s[42:43], 0, v6
	s_lshl_b32 s9, s24, 12
	s_add_u32 s12, s20, s9
	v_cndmask_b32_e64 v4, v5, v4, s[42:43]
	v_cndmask_b32_e64 v2, v3, v2, s[42:43]
	v_lshlrev_b32_e32 v3, 8, v6
	v_lshlrev_b32_e32 v5, 2, v0
	v_or_b32_e32 v6, v3, v5
	v_add_u32_e32 v7, v8, v6
	v_add_u32_e32 v6, v10, v6
	ds_write_b32 v7, v4
	ds_write_b32 v6, v2
	v_or_b32_e32 v6, 7, v0
	v_and_b32_e32 v7, 56, v1
	v_cndmask_b32_e32 v6, v7, v6, vcc
	v_and_or_b32 v6, v197, 64, v6
	v_lshlrev_b32_e32 v6, 2, v6
	ds_bpermute_b32 v6, v6, v4
	s_addc_u32 s13, s21, 0
	v_add3_u32 v3, v9, v3, v5
	s_ashr_i32 s24, s8, 4
	v_lshlrev_b32_e32 v164, 4, v0
	s_waitcnt lgkmcnt(0)
	v_sub_f32_e32 v4, v6, v4
	v_mul_f32_e32 v4, 0x3fb8aa3b, v4
	v_exp_f32_e32 v4, v4
	v_and_b32_e32 v97, 15, v1
	v_lshlrev_b32_e32 v105, 5, v11
	v_or_b32_e32 v106, v105, v97
	v_mul_f32_e32 v2, v2, v4
	ds_write_b32 v3, v2
	v_lshl_add_u32 v2, v11, 1, s24
	v_ashrrev_i32_e32 v3, 31, v2
	v_lshlrev_b64 v[6:7], 14, v[2:3]
	v_or_b32_e32 v2, 1, v2
	v_ashrrev_i32_e32 v3, 31, v2
	v_lshl_add_u64 v[4:5], s[12:13], 0, v[164:165]
	v_lshlrev_b64 v[2:3], 14, v[2:3]
	v_lshl_add_u64 v[6:7], v[4:5], 0, v[6:7]
	v_lshl_add_u64 v[2:3], v[4:5], 0, v[2:3]
	s_waitcnt vmcnt(0)
	v_mov_b32_e32 v16, v140
	v_mov_b32_e32 v17, v141
	v_mov_b32_e32 v18, v142
	v_mov_b32_e32 v19, v143
	v_mov_b32_e32 v20, v144
	v_mov_b32_e32 v21, v145
	v_mov_b32_e32 v22, v146
	v_mov_b32_e32 v23, v147
	v_mov_b32_e32 v24, v148
	v_mov_b32_e32 v25, v149
	v_mov_b32_e32 v26, v150
	v_mov_b32_e32 v27, v151
	v_mov_b32_e32 v28, v152
	v_mov_b32_e32 v29, v153
	v_mov_b32_e32 v30, v154
	v_mov_b32_e32 v31, v155
	v_mov_b32_e32 v32, v156
	v_mov_b32_e32 v33, v157
	v_mov_b32_e32 v34, v158
	v_mov_b32_e32 v35, v159
	v_mov_b32_e32 v36, v160
	v_mov_b32_e32 v37, v161
	v_mov_b32_e32 v38, v162
	v_mov_b32_e32 v39, v163
	v_mov_b32_e32 v40, v172
	v_mov_b32_e32 v41, v173
	v_mov_b32_e32 v42, v174
	v_mov_b32_e32 v43, v175
	v_mov_b32_e32 v44, v176
	v_mov_b32_e32 v45, v177
	v_mov_b32_e32 v46, v178
	v_mov_b32_e32 v47, v179
	v_lshl_add_u32 v107, v106, 2, 0
	v_lshrrev_b32_e32 v102, 4, v0
	v_add_u32_e32 v2, 0xd000, v107
	s_waitcnt lgkmcnt(0)
	s_barrier
	ds_read2_b32 v[98:99], v2 offset1:16
	ds_read2_b32 v[100:101], v2 offset0:128 offset1:144
	v_lshlrev_b32_e32 v104, 3, v102
	v_mul_u32_u24_e32 v2, 0x110, v97
	v_readlane_b32 s2, v249, 56
	v_lshlrev_b32_e32 v108, 2, v102
	v_and_b32_e32 v3, 48, v0
	v_add3_u32 v109, v2, v104, s2
	v_readlane_b32 s2, v249, 55
	s_movk_i32 s12, 0x60
	v_and_b32_e32 v1, 48, v1
	v_add_u32_e32 v110, s2, v3
	v_sub_u32_e32 v3, v108, v106
	v_add_u32_e32 v111, 3, v3
	v_add_u32_e32 v112, 2, v3
	v_add_u32_e32 v113, 1, v3
	v_bitop3_b32 v3, v0, s12, 64 bitop3:0xc8
	v_and_b32_e32 v0, 32, v0
	v_add_u32_e32 v116, s96, v0
	v_mov_b32_e32 v0, 0
	s_mov_b32 s9, 0
	v_or_b32_e32 v103, 16, v106
	v_add_u32_e32 v114, s96, v3
	v_sub_u32_e32 v115, v106, v108
	v_add3_u32 v117, v2, v1, 0
	v_mov_b32_e32 v1, v0
	v_mov_b32_e32 v2, v0
	v_mov_b32_e32 v3, v0
	v_mov_b32_e32 v48, v0
	v_mov_b32_e32 v49, v0
	v_mov_b32_e32 v50, v0
	v_mov_b32_e32 v51, v0
	v_mov_b32_e32 v4, v0
	v_mov_b32_e32 v5, v0
	v_mov_b32_e32 v6, v0
	v_mov_b32_e32 v7, v0
	v_mov_b32_e32 v52, v0
	v_mov_b32_e32 v53, v0
	v_mov_b32_e32 v54, v0
	v_mov_b32_e32 v55, v0
	v_mov_b32_e32 v8, v0
	v_mov_b32_e32 v9, v0
	v_mov_b32_e32 v10, v0
	v_mov_b32_e32 v11, v0
	v_mov_b32_e32 v56, v0
	v_mov_b32_e32 v57, v0
	v_mov_b32_e32 v58, v0
	v_mov_b32_e32 v59, v0
	v_mov_b32_e32 v12, v0
	v_mov_b32_e32 v13, v0
	v_mov_b32_e32 v14, v0
	v_mov_b32_e32 v15, v0
	v_mov_b32_e32 v60, v0
	v_mov_b32_e32 v61, v0
	v_mov_b32_e32 v62, v0
	v_mov_b32_e32 v63, v0
	s_branch .LBB0_431
